# conv tap loop 4-deep raw-token prefetch (unrolled x4, four register sets; next_free_vgpr 248, same allocation)
# baseline (speedup 1.0000x reference)
; __device__ __forceinline__ void conv_item(KP p, LAS unsigned char* lds, int l, int tile) {
;     ...
;     const int tbase = tile * 64, c0 = 2 * tid;
;     const bf16_t* hm = HM + c0;
;     f32x2 w[31];
; #pragma unroll
;     for (int j = 0; j < 31; ++j) w[j] = *(const f32x2*)(p->in[10] + (size_t)(l * 31 + j) * 1024 + c0);
;     const f32x2 cb = *(const f32x2*)(p->in[11] + l * 1024 + c0);
;     f32x2 g[34];
; #pragma unroll
;     for (int i = 0; i < 30; ++i) g[i] = glu_at(hm, tbase - 30 + i);
;     unsigned nv[4];
; #pragma unroll
;     for (int q = 0; q < 4; ++q) nv[q] = *(const unsigned*)(hm + (size_t)(tbase + q) * HMW + C_GLU);
;     const float* lng = p->in[12] + l * 1024; const float* lnb = p->in[13] + l * 1024;
.LBB0_460:
	s_mul_i32 s6, s6, 0x84000
	v_lshl_add_u64 v[4:5], s[6:7], 1, v[82:83]
	v_add_co_u32_e32 v8, vcc, 0x3000, v4
	v_lshl_add_u32 v175, v2, 2, 0
	s_nop 0
	v_addc_co_u32_e32 v9, vcc, 0, v5, vcc
	global_load_dword v174, v[8:9], off offset:512
	v_add_co_u32_e32 v8, vcc, 0x7000, v4
	v_and_b32_e32 v2, 64, v172
	s_nop 0
	v_addc_co_u32_e32 v9, vcc, 0, v5, vcc
	global_load_dword v177, v[8:9], off offset:1024
	v_add_co_u32_e32 v8, vcc, 0xb000, v4
	v_add_u32_e32 v2, 64, v2
	s_nop 0
	v_addc_co_u32_e32 v9, vcc, 0, v5, vcc
	v_add_co_u32_e32 v4, vcc, 0xf000, v4
	global_load_dword v184, v[8:9], off offset:1536
	s_nop 0
	v_addc_co_u32_e32 v5, vcc, 0, v5, vcc
	global_load_dword v185, v[4:5], off offset:2048
	s_mov_b64 s[40:41], 0x4200
	v_lshl_add_u64 v[8:9], v[4:5], 0, s[40:41]
	global_load_dword v236, v[8:9], off offset:2048
	v_lshl_add_u64 v[8:9], v[8:9], 0, s[40:41]
	global_load_dword v237, v[8:9], off offset:2048
	v_lshl_add_u64 v[8:9], v[8:9], 0, s[40:41]
	global_load_dword v238, v[8:9], off offset:2048
	v_lshl_add_u64 v[8:9], v[8:9], 0, s[40:41]
	global_load_dword v239, v[8:9], off offset:2048
	v_lshl_add_u64 v[8:9], v[8:9], 0, s[40:41]
	global_load_dword v242, v[8:9], off offset:2048
	v_lshl_add_u64 v[8:9], v[8:9], 0, s[40:41]
	global_load_dword v243, v[8:9], off offset:2048
	v_lshl_add_u64 v[8:9], v[8:9], 0, s[40:41]
	global_load_dword v244, v[8:9], off offset:2048
	v_lshl_add_u64 v[8:9], v[8:9], 0, s[40:41]
	global_load_dword v245, v[8:9], off offset:2048
	v_lshl_add_u64 v[8:9], v[8:9], 0, s[40:41]
	global_load_dword v246, v[8:9], off offset:2048
	v_lshl_add_u64 v[8:9], v[8:9], 0, s[40:41]
	global_load_dword v247, v[8:9], off offset:2048
	v_lshl_add_u64 v[8:9], v[8:9], 0, s[40:41]
	global_load_dword v194, v[8:9], off offset:2048
	v_lshl_add_u64 v[8:9], v[8:9], 0, s[40:41]
	global_load_dword v195, v[8:9], off offset:2048
	v_xor_b32_e32 v4, 1, v172
	v_cmp_lt_i32_e32 vcc, v4, v2
	s_load_dwordx4 s[40:43], s[0:1], 0x60
	v_and_b32_e32 v3, 63, v6
	v_cndmask_b32_e32 v4, v172, v4, vcc
	v_lshlrev_b32_e32 v176, 2, v4
	v_xor_b32_e32 v4, 2, v172
	v_cmp_lt_i32_e32 vcc, v4, v2
	s_waitcnt lgkmcnt(0)
	s_add_u32 s40, s40, s44
	s_addc_u32 s41, s41, s45
	v_cndmask_b32_e32 v4, v172, v4, vcc
	v_lshlrev_b32_e32 v178, 2, v4
	v_xor_b32_e32 v4, 4, v172
	v_cmp_lt_i32_e32 vcc, v4, v2
	s_add_u32 s42, s42, s44
	s_addc_u32 s43, s43, s45
	v_cndmask_b32_e32 v4, v172, v4, vcc
	v_lshlrev_b32_e32 v179, 2, v4
	v_xor_b32_e32 v4, 8, v172
	v_cmp_lt_i32_e32 vcc, v4, v2
	s_ashr_i32 s6, s24, 4
	s_and_b32 s46, s6, -4
	v_cndmask_b32_e32 v4, v172, v4, vcc
	v_lshlrev_b32_e32 v180, 2, v4
	v_xor_b32_e32 v4, 16, v172
	s_lshl_b32 s6, s6, 12
	v_lshlrev_b32_e32 v0, 4, v3
	v_cmp_lt_i32_e32 vcc, v4, v2
	s_and_b32 s6, s6, 0xffffc000
	v_lshl_add_u64 v[152:153], s[40:41], 0, v[0:1]
	v_cndmask_b32_e32 v4, v172, v4, vcc
	s_add_i32 s6, s6, 0
	v_readlane_b32 s40, v240, 39
	v_lshlrev_b32_e32 v181, 2, v4
	v_xor_b32_e32 v4, 32, v172
	v_lshl_add_u64 v[154:155], s[42:43], 0, v[0:1]
	v_add_u32_e32 v183, s6, v0
	v_lshlrev_b32_e32 v0, 3, v3
	v_readlane_b32 s41, v240, 40
	v_cmp_lt_i32_e32 vcc, v4, v2
	s_lshl_b32 s62, s92, 6
	v_lshl_add_u64 v[156:157], s[40:41], 0, v[0:1]
	v_readlane_b32 s40, v240, 41
	v_cndmask_b32_e32 v2, v172, v4, vcc
	v_readlane_b32 s41, v240, 42
	s_mov_b32 s63, 0
	v_lshlrev_b32_e32 v182, 2, v2
	s_add_i32 s47, s62, 0xffff9004
	s_ashr_i32 s61, s46, 31
	s_addk_i32 s62, 0x9000
	v_lshl_add_u64 v[158:159], s[40:41], 0, v[0:1]
	global_load_dwordx4 v[196:199], v[152:153], off
	global_load_dwordx4 v[200:203], v[154:155], off
	global_load_dwordx4 v[204:207], v[152:153], off offset:1024
	global_load_dwordx4 v[208:211], v[154:155], off offset:1024
	global_load_dwordx4 v[212:215], v[152:153], off offset:2048
	global_load_dwordx4 v[216:219], v[154:155], off offset:2048
	global_load_dwordx4 v[220:223], v[152:153], off offset:3072
	global_load_dwordx4 v[224:227], v[154:155], off offset:3072
	s_mov_b64 s[44:45], -1
	s_mov_b64 s[42:43], 0

; #define LAS __attribute__((address_space(3)))
; __device__ __forceinline__ float bflo(unsigned w) { return __uint_as_float(w << 16); }
; __device__ __forceinline__ float bfhi(unsigned w) { return __uint_as_float(w & 0xffff0000u); }
; __device__ __forceinline__ void conv_item(KP p, LAS unsigned char* lds, int l, int tile) {
;     ...
;     for (int blk = 0; blk < 8; ++blk) {
; #pragma unroll
;         for (int q = 0; q < 4; ++q) g[30 + q] = (f32x2){bflo(nv[q]), bfhi(nv[q])};
;         { const int tn = (hh == 1 && blk == 7) ? t0 + blk * 4 : t0 + (blk + 1) * 4;
; #pragma unroll
;           for (int q = 0; q < 4; ++q) nv[q] = *(const unsigned*)(hm + (size_t)(tn + q) * HMW + C_GLU); }
;         f32x2 y[4] = {cb, cb, cb, cb};
; #pragma unroll
;         for (int j = 0; j < 31; ++j)
; #pragma unroll
;             for (int q = 0; q < 4; ++q) y[q] += w[j] * g[q + j];
; #pragma unroll
;         for (int q = 0; q < 4; ++q) *(LAS f32x2*)(ybuf + (blk * 4 + q) * 1024 + c0) = y[q];
; #pragma unroll
;         for (int i = 0; i < 30; ++i) g[i] = g[i + 4];
;     }
.LBB0_462:
	s_add_i32 s6, s45, 12
	s_min_i32 s6, s6, s44
	s_mulk_i32 s6, 0x2100
	v_lshl_add_u64 v[10:11], s[6:7], 1, v[82:83]
	v_add_co_u32_e32 v10, vcc, s52, v10
	s_add_i32 s66, s6, 0x2100
	s_nop 0
	v_addc_co_u32_e32 v11, vcc, 0, v11, vcc
	s_mov_b32 s67, s7
	v_mov_b64_e32 v[6:7], v[88:89]
	v_mov_b64_e32 v[88:89], v[96:97]
	v_mov_b64_e32 v[96:97], v[104:105]
	v_mov_b64_e32 v[104:105], v[112:113]
	v_mov_b64_e32 v[112:113], v[120:121]
	v_mov_b64_e32 v[120:121], v[128:129]
	v_mov_b64_e32 v[128:129], v[136:137]
	s_waitcnt vmcnt(15)
	v_lshlrev_b32_e32 v136, 16, v174
	v_and_b32_e32 v137, 0xffff0000, v174
	global_load_dword v174, v[10:11], off offset:512
	v_lshl_add_u64 v[10:11], s[66:67], 1, v[82:83]
	v_add_co_u32_e32 v10, vcc, s52, v10
	s_add_i32 s66, s6, 0x4200
	s_nop 0
	v_addc_co_u32_e32 v11, vcc, 0, v11, vcc
	v_mov_b64_e32 v[8:9], v[90:91]
	v_mov_b64_e32 v[90:91], v[98:99]
	v_mov_b64_e32 v[98:99], v[106:107]
	v_mov_b64_e32 v[106:107], v[114:115]
	v_mov_b64_e32 v[114:115], v[122:123]
	v_mov_b64_e32 v[122:123], v[130:131]
	v_mov_b64_e32 v[130:131], v[138:139]
	s_waitcnt vmcnt(15)
	v_lshlrev_b32_e32 v138, 16, v177
	v_and_b32_e32 v139, 0xffff0000, v177
	global_load_dword v177, v[10:11], off offset:512
	v_lshl_add_u64 v[10:11], s[66:67], 1, v[82:83]
	v_add_co_u32_e32 v10, vcc, s52, v10
	s_addk_i32 s6, 0x6300
	s_nop 0
	v_addc_co_u32_e32 v11, vcc, 0, v11, vcc
	v_mov_b64_e32 v[2:3], v[84:85]
	v_mov_b64_e32 v[84:85], v[92:93]
	v_mov_b64_e32 v[92:93], v[100:101]
	v_mov_b64_e32 v[100:101], v[108:109]
	v_mov_b64_e32 v[108:109], v[116:117]
	v_mov_b64_e32 v[116:117], v[124:125]
	v_mov_b64_e32 v[124:125], v[132:133]
	v_mov_b64_e32 v[132:133], v[148:149]
	s_waitcnt vmcnt(15)
	v_lshlrev_b32_e32 v148, 16, v184
	v_and_b32_e32 v149, 0xffff0000, v184
	global_load_dword v184, v[10:11], off offset:512
	v_lshl_add_u64 v[10:11], s[6:7], 1, v[82:83]
	v_add_co_u32_e32 v10, vcc, s52, v10
	v_mov_b64_e32 v[4:5], v[86:87]
	s_nop 0
	v_addc_co_u32_e32 v11, vcc, 0, v11, vcc
	v_mov_b64_e32 v[86:87], v[94:95]
	v_mov_b64_e32 v[94:95], v[102:103]
	v_mov_b64_e32 v[102:103], v[110:111]
	v_mov_b64_e32 v[110:111], v[118:119]
	v_mov_b64_e32 v[118:119], v[126:127]
	v_mov_b64_e32 v[126:127], v[134:135]
	v_mov_b64_e32 v[134:135], v[150:151]
	s_waitcnt vmcnt(15)
	v_lshlrev_b32_e32 v150, 16, v185
	v_and_b32_e32 v151, 0xffff0000, v185
	global_load_dword v185, v[10:11], off offset:512
	v_pk_fma_f32 v[2:3], v[18:19], v[2:3], v[80:81]
	v_pk_fma_f32 v[10:11], v[18:19], v[4:5], v[80:81]
	v_pk_fma_f32 v[12:13], v[18:19], v[6:7], v[80:81]
	v_pk_fma_f32 v[14:15], v[18:19], v[8:9], v[80:81]
	v_pk_fma_f32 v[2:3], v[20:21], v[4:5], v[2:3]
	v_pk_fma_f32 v[4:5], v[20:21], v[6:7], v[10:11]
	v_pk_fma_f32 v[10:11], v[20:21], v[8:9], v[12:13]
	v_pk_fma_f32 v[12:13], v[20:21], v[84:85], v[14:15]
	v_pk_fma_f32 v[2:3], v[22:23], v[6:7], v[2:3]
	v_pk_fma_f32 v[4:5], v[22:23], v[8:9], v[4:5]
	v_pk_fma_f32 v[6:7], v[22:23], v[84:85], v[10:11]
	v_pk_fma_f32 v[10:11], v[22:23], v[86:87], v[12:13]
	v_pk_fma_f32 v[2:3], v[24:25], v[8:9], v[2:3]
	v_pk_fma_f32 v[4:5], v[24:25], v[84:85], v[4:5]
	v_pk_fma_f32 v[6:7], v[24:25], v[86:87], v[6:7]
	v_pk_fma_f32 v[8:9], v[24:25], v[88:89], v[10:11]
	v_pk_fma_f32 v[2:3], v[26:27], v[84:85], v[2:3]
	v_pk_fma_f32 v[4:5], v[26:27], v[86:87], v[4:5]
	v_pk_fma_f32 v[6:7], v[26:27], v[88:89], v[6:7]
	v_pk_fma_f32 v[8:9], v[26:27], v[90:91], v[8:9]
	v_pk_fma_f32 v[2:3], v[28:29], v[86:87], v[2:3]
	v_pk_fma_f32 v[4:5], v[28:29], v[88:89], v[4:5]
	v_pk_fma_f32 v[6:7], v[28:29], v[90:91], v[6:7]
	v_pk_fma_f32 v[8:9], v[28:29], v[92:93], v[8:9]
	v_pk_fma_f32 v[2:3], v[30:31], v[88:89], v[2:3]
	v_pk_fma_f32 v[4:5], v[30:31], v[90:91], v[4:5]
	v_pk_fma_f32 v[6:7], v[30:31], v[92:93], v[6:7]
	v_pk_fma_f32 v[8:9], v[30:31], v[94:95], v[8:9]
	v_pk_fma_f32 v[2:3], v[32:33], v[90:91], v[2:3]
	v_pk_fma_f32 v[4:5], v[32:33], v[92:93], v[4:5]
	v_pk_fma_f32 v[6:7], v[32:33], v[94:95], v[6:7]
	v_pk_fma_f32 v[8:9], v[32:33], v[96:97], v[8:9]
	v_pk_fma_f32 v[2:3], v[34:35], v[92:93], v[2:3]
	v_pk_fma_f32 v[4:5], v[34:35], v[94:95], v[4:5]
	v_pk_fma_f32 v[6:7], v[34:35], v[96:97], v[6:7]
	v_pk_fma_f32 v[8:9], v[34:35], v[98:99], v[8:9]
	v_pk_fma_f32 v[2:3], v[36:37], v[94:95], v[2:3]
	v_pk_fma_f32 v[4:5], v[36:37], v[96:97], v[4:5]
	v_pk_fma_f32 v[6:7], v[36:37], v[98:99], v[6:7]
	v_pk_fma_f32 v[8:9], v[36:37], v[100:101], v[8:9]
	v_pk_fma_f32 v[2:3], v[38:39], v[96:97], v[2:3]
	v_pk_fma_f32 v[4:5], v[38:39], v[98:99], v[4:5]
	v_pk_fma_f32 v[6:7], v[38:39], v[100:101], v[6:7]
	v_pk_fma_f32 v[8:9], v[38:39], v[102:103], v[8:9]
	v_pk_fma_f32 v[2:3], v[40:41], v[98:99], v[2:3]
	v_pk_fma_f32 v[4:5], v[40:41], v[100:101], v[4:5]
	v_pk_fma_f32 v[6:7], v[40:41], v[102:103], v[6:7]
	v_pk_fma_f32 v[8:9], v[40:41], v[104:105], v[8:9]
	v_pk_fma_f32 v[2:3], v[42:43], v[100:101], v[2:3]
	v_pk_fma_f32 v[4:5], v[42:43], v[102:103], v[4:5]
	v_pk_fma_f32 v[6:7], v[42:43], v[104:105], v[6:7]
	v_pk_fma_f32 v[8:9], v[42:43], v[106:107], v[8:9]
	v_pk_fma_f32 v[2:3], v[44:45], v[102:103], v[2:3]
	v_pk_fma_f32 v[4:5], v[44:45], v[104:105], v[4:5]
	v_pk_fma_f32 v[6:7], v[44:45], v[106:107], v[6:7]
	v_pk_fma_f32 v[8:9], v[44:45], v[108:109], v[8:9]
	v_pk_fma_f32 v[2:3], v[46:47], v[104:105], v[2:3]
	v_pk_fma_f32 v[4:5], v[46:47], v[106:107], v[4:5]
	v_pk_fma_f32 v[6:7], v[46:47], v[108:109], v[6:7]
	v_pk_fma_f32 v[8:9], v[46:47], v[110:111], v[8:9]
	v_pk_fma_f32 v[2:3], v[48:49], v[106:107], v[2:3]
	v_pk_fma_f32 v[4:5], v[48:49], v[108:109], v[4:5]
	v_pk_fma_f32 v[6:7], v[48:49], v[110:111], v[6:7]
	v_pk_fma_f32 v[8:9], v[48:49], v[112:113], v[8:9]
	v_pk_fma_f32 v[2:3], v[50:51], v[108:109], v[2:3]
; #define LAS __attribute__((address_space(3)))
; __device__ __forceinline__ void conv_item(KP p, LAS unsigned char* lds, int l, int tile) {
;     ...
;         for (int j = 0; j < 31; ++j)
; #pragma unroll
;             for (int q = 0; q < 4; ++q) y[q] += w[j] * g[q + j];
; #pragma unroll
;         for (int q = 0; q < 4; ++q) *(LAS f32x2*)(ybuf + (blk * 4 + q) * 1024 + c0) = y[q];
; #pragma unroll
;         for (int i = 0; i < 30; ++i) g[i] = g[i + 4];
;     }
	v_pk_fma_f32 v[4:5], v[50:51], v[110:111], v[4:5]
	v_pk_fma_f32 v[6:7], v[50:51], v[112:113], v[6:7]
	v_pk_fma_f32 v[8:9], v[50:51], v[114:115], v[8:9]
	v_pk_fma_f32 v[2:3], v[52:53], v[110:111], v[2:3]
	v_pk_fma_f32 v[4:5], v[52:53], v[112:113], v[4:5]
	v_pk_fma_f32 v[6:7], v[52:53], v[114:115], v[6:7]
	v_pk_fma_f32 v[8:9], v[52:53], v[116:117], v[8:9]
	v_pk_fma_f32 v[2:3], v[54:55], v[112:113], v[2:3]
	v_pk_fma_f32 v[4:5], v[54:55], v[114:115], v[4:5]
	v_pk_fma_f32 v[6:7], v[54:55], v[116:117], v[6:7]
	v_pk_fma_f32 v[8:9], v[54:55], v[118:119], v[8:9]
	v_pk_fma_f32 v[2:3], v[56:57], v[114:115], v[2:3]
	v_pk_fma_f32 v[4:5], v[56:57], v[116:117], v[4:5]
	v_pk_fma_f32 v[6:7], v[56:57], v[118:119], v[6:7]
	v_pk_fma_f32 v[8:9], v[56:57], v[120:121], v[8:9]
	v_pk_fma_f32 v[2:3], v[58:59], v[116:117], v[2:3]
	v_pk_fma_f32 v[4:5], v[58:59], v[118:119], v[4:5]
	v_pk_fma_f32 v[6:7], v[58:59], v[120:121], v[6:7]
	v_pk_fma_f32 v[8:9], v[58:59], v[122:123], v[8:9]
	v_pk_fma_f32 v[2:3], v[60:61], v[118:119], v[2:3]
	v_pk_fma_f32 v[4:5], v[60:61], v[120:121], v[4:5]
	v_pk_fma_f32 v[6:7], v[60:61], v[122:123], v[6:7]
	v_pk_fma_f32 v[8:9], v[60:61], v[124:125], v[8:9]
	v_pk_fma_f32 v[2:3], v[62:63], v[120:121], v[2:3]
	v_pk_fma_f32 v[4:5], v[62:63], v[122:123], v[4:5]
	v_pk_fma_f32 v[6:7], v[62:63], v[124:125], v[6:7]
	v_pk_fma_f32 v[8:9], v[62:63], v[126:127], v[8:9]
	v_pk_fma_f32 v[2:3], v[64:65], v[122:123], v[2:3]
	v_pk_fma_f32 v[4:5], v[64:65], v[124:125], v[4:5]
	v_pk_fma_f32 v[6:7], v[64:65], v[126:127], v[6:7]
	v_pk_fma_f32 v[8:9], v[64:65], v[128:129], v[8:9]
	v_pk_fma_f32 v[2:3], v[66:67], v[124:125], v[2:3]
	v_pk_fma_f32 v[4:5], v[66:67], v[126:127], v[4:5]
	v_pk_fma_f32 v[6:7], v[66:67], v[128:129], v[6:7]
	v_pk_fma_f32 v[8:9], v[66:67], v[130:131], v[8:9]
	v_pk_fma_f32 v[2:3], v[68:69], v[126:127], v[2:3]
	v_pk_fma_f32 v[4:5], v[68:69], v[128:129], v[4:5]
	v_pk_fma_f32 v[6:7], v[68:69], v[130:131], v[6:7]
	v_pk_fma_f32 v[8:9], v[68:69], v[132:133], v[8:9]
	v_pk_fma_f32 v[2:3], v[70:71], v[128:129], v[2:3]
	v_pk_fma_f32 v[4:5], v[70:71], v[130:131], v[4:5]
	v_pk_fma_f32 v[6:7], v[70:71], v[132:133], v[6:7]
	v_pk_fma_f32 v[8:9], v[70:71], v[134:135], v[8:9]
	v_pk_fma_f32 v[2:3], v[72:73], v[130:131], v[2:3]
	v_pk_fma_f32 v[4:5], v[72:73], v[132:133], v[4:5]
	v_pk_fma_f32 v[6:7], v[72:73], v[134:135], v[6:7]
	v_pk_fma_f32 v[8:9], v[72:73], v[136:137], v[8:9]
	v_pk_fma_f32 v[2:3], v[74:75], v[132:133], v[2:3]
	v_pk_fma_f32 v[4:5], v[74:75], v[134:135], v[4:5]
	v_pk_fma_f32 v[6:7], v[74:75], v[136:137], v[6:7]
	v_pk_fma_f32 v[8:9], v[74:75], v[138:139], v[8:9]
	v_pk_fma_f32 v[2:3], v[76:77], v[134:135], v[2:3]
	v_pk_fma_f32 v[4:5], v[76:77], v[136:137], v[4:5]
	v_add_u32_e32 v0, s64, v175
	s_add_i32 s45, s45, 4
	s_addk_i32 s64, 0x4000
	v_pk_fma_f32 v[6:7], v[76:77], v[138:139], v[6:7]
	v_pk_fma_f32 v[8:9], v[76:77], v[148:149], v[8:9]
	v_pk_fma_f32 v[2:3], v[78:79], v[136:137], v[2:3]
	v_pk_fma_f32 v[4:5], v[78:79], v[138:139], v[4:5]
	v_pk_fma_f32 v[6:7], v[78:79], v[148:149], v[6:7]
	v_pk_fma_f32 v[8:9], v[78:79], v[150:151], v[8:9]
	ds_write2st64_b64 v0, v[2:3], v[4:5] offset1:8
	ds_write2st64_b64 v0, v[6:7], v[8:9] offset0:16 offset1:24
	s_add_i32 s6, s45, 12
	s_min_i32 s6, s6, s44
	s_mulk_i32 s6, 0x2100
	v_lshl_add_u64 v[10:11], s[6:7], 1, v[82:83]
	v_add_co_u32_e32 v10, vcc, s52, v10
	s_add_i32 s66, s6, 0x2100
	s_nop 0
	v_addc_co_u32_e32 v11, vcc, 0, v11, vcc
	s_mov_b32 s67, s7
	v_mov_b64_e32 v[6:7], v[88:89]
	v_mov_b64_e32 v[88:89], v[96:97]
	v_mov_b64_e32 v[96:97], v[104:105]
	v_mov_b64_e32 v[104:105], v[112:113]
	v_mov_b64_e32 v[112:113], v[120:121]
	v_mov_b64_e32 v[120:121], v[128:129]
	v_mov_b64_e32 v[128:129], v[136:137]
	s_waitcnt vmcnt(15)
	v_lshlrev_b32_e32 v136, 16, v236
	v_and_b32_e32 v137, 0xffff0000, v236
	global_load_dword v236, v[10:11], off offset:512
	v_lshl_add_u64 v[10:11], s[66:67], 1, v[82:83]
	v_add_co_u32_e32 v10, vcc, s52, v10
	s_add_i32 s66, s6, 0x4200
	s_nop 0
	v_addc_co_u32_e32 v11, vcc, 0, v11, vcc
	v_mov_b64_e32 v[8:9], v[90:91]
	v_mov_b64_e32 v[90:91], v[98:99]
	v_mov_b64_e32 v[98:99], v[106:107]
	v_mov_b64_e32 v[106:107], v[114:115]
	v_mov_b64_e32 v[114:115], v[122:123]
	v_mov_b64_e32 v[122:123], v[130:131]
	v_mov_b64_e32 v[130:131], v[138:139]
	s_waitcnt vmcnt(15)
	v_lshlrev_b32_e32 v138, 16, v237
	v_and_b32_e32 v139, 0xffff0000, v237
	global_load_dword v237, v[10:11], off offset:512
	v_lshl_add_u64 v[10:11], s[66:67], 1, v[82:83]
	v_add_co_u32_e32 v10, vcc, s52, v10
	s_addk_i32 s6, 0x6300
	s_nop 0
	v_addc_co_u32_e32 v11, vcc, 0, v11, vcc
	v_mov_b64_e32 v[2:3], v[84:85]
	v_mov_b64_e32 v[84:85], v[92:93]
	v_mov_b64_e32 v[92:93], v[100:101]
	v_mov_b64_e32 v[100:101], v[108:109]
	v_mov_b64_e32 v[108:109], v[116:117]
	v_mov_b64_e32 v[116:117], v[124:125]
	v_mov_b64_e32 v[124:125], v[132:133]
	v_mov_b64_e32 v[132:133], v[148:149]
	s_waitcnt vmcnt(15)
	v_lshlrev_b32_e32 v148, 16, v238
	v_and_b32_e32 v149, 0xffff0000, v238
	global_load_dword v238, v[10:11], off offset:512
	v_lshl_add_u64 v[10:11], s[6:7], 1, v[82:83]
	v_add_co_u32_e32 v10, vcc, s52, v10
	v_mov_b64_e32 v[4:5], v[86:87]
	s_nop 0
	v_addc_co_u32_e32 v11, vcc, 0, v11, vcc
	v_mov_b64_e32 v[86:87], v[94:95]
	v_mov_b64_e32 v[94:95], v[102:103]
	v_mov_b64_e32 v[102:103], v[110:111]
	v_mov_b64_e32 v[110:111], v[118:119]
	v_mov_b64_e32 v[118:119], v[126:127]
	v_mov_b64_e32 v[126:127], v[134:135]
	v_mov_b64_e32 v[134:135], v[150:151]
	s_waitcnt vmcnt(15)
; __device__ __forceinline__ void conv_item(KP p, LAS unsigned char* lds, int l, int tile) {
;     ...
;         for (int j = 0; j < 31; ++j)
; #pragma unroll
;             for (int q = 0; q < 4; ++q) y[q] += w[j] * g[q + j];
	v_lshlrev_b32_e32 v150, 16, v239
	v_and_b32_e32 v151, 0xffff0000, v239
	global_load_dword v239, v[10:11], off offset:512
	v_pk_fma_f32 v[2:3], v[18:19], v[2:3], v[80:81]
	v_pk_fma_f32 v[10:11], v[18:19], v[4:5], v[80:81]
	v_pk_fma_f32 v[12:13], v[18:19], v[6:7], v[80:81]
	v_pk_fma_f32 v[14:15], v[18:19], v[8:9], v[80:81]
	v_pk_fma_f32 v[2:3], v[20:21], v[4:5], v[2:3]
	v_pk_fma_f32 v[4:5], v[20:21], v[6:7], v[10:11]
	v_pk_fma_f32 v[10:11], v[20:21], v[8:9], v[12:13]
	v_pk_fma_f32 v[12:13], v[20:21], v[84:85], v[14:15]
	v_pk_fma_f32 v[2:3], v[22:23], v[6:7], v[2:3]
	v_pk_fma_f32 v[4:5], v[22:23], v[8:9], v[4:5]
	v_pk_fma_f32 v[6:7], v[22:23], v[84:85], v[10:11]
	v_pk_fma_f32 v[10:11], v[22:23], v[86:87], v[12:13]
	v_pk_fma_f32 v[2:3], v[24:25], v[8:9], v[2:3]
	v_pk_fma_f32 v[4:5], v[24:25], v[84:85], v[4:5]
	v_pk_fma_f32 v[6:7], v[24:25], v[86:87], v[6:7]
	v_pk_fma_f32 v[8:9], v[24:25], v[88:89], v[10:11]
	v_pk_fma_f32 v[2:3], v[26:27], v[84:85], v[2:3]
	v_pk_fma_f32 v[4:5], v[26:27], v[86:87], v[4:5]
	v_pk_fma_f32 v[6:7], v[26:27], v[88:89], v[6:7]
	v_pk_fma_f32 v[8:9], v[26:27], v[90:91], v[8:9]
	v_pk_fma_f32 v[2:3], v[28:29], v[86:87], v[2:3]
	v_pk_fma_f32 v[4:5], v[28:29], v[88:89], v[4:5]
	v_pk_fma_f32 v[6:7], v[28:29], v[90:91], v[6:7]
	v_pk_fma_f32 v[8:9], v[28:29], v[92:93], v[8:9]
	v_pk_fma_f32 v[2:3], v[30:31], v[88:89], v[2:3]
	v_pk_fma_f32 v[4:5], v[30:31], v[90:91], v[4:5]
	v_pk_fma_f32 v[6:7], v[30:31], v[92:93], v[6:7]
	v_pk_fma_f32 v[8:9], v[30:31], v[94:95], v[8:9]
	v_pk_fma_f32 v[2:3], v[32:33], v[90:91], v[2:3]
	v_pk_fma_f32 v[4:5], v[32:33], v[92:93], v[4:5]
	v_pk_fma_f32 v[6:7], v[32:33], v[94:95], v[6:7]
	v_pk_fma_f32 v[8:9], v[32:33], v[96:97], v[8:9]
	v_pk_fma_f32 v[2:3], v[34:35], v[92:93], v[2:3]
	v_pk_fma_f32 v[4:5], v[34:35], v[94:95], v[4:5]
	v_pk_fma_f32 v[6:7], v[34:35], v[96:97], v[6:7]
	v_pk_fma_f32 v[8:9], v[34:35], v[98:99], v[8:9]
	v_pk_fma_f32 v[2:3], v[36:37], v[94:95], v[2:3]
	v_pk_fma_f32 v[4:5], v[36:37], v[96:97], v[4:5]
	v_pk_fma_f32 v[6:7], v[36:37], v[98:99], v[6:7]
	v_pk_fma_f32 v[8:9], v[36:37], v[100:101], v[8:9]
	v_pk_fma_f32 v[2:3], v[38:39], v[96:97], v[2:3]
	v_pk_fma_f32 v[4:5], v[38:39], v[98:99], v[4:5]
	v_pk_fma_f32 v[6:7], v[38:39], v[100:101], v[6:7]
	v_pk_fma_f32 v[8:9], v[38:39], v[102:103], v[8:9]
	v_pk_fma_f32 v[2:3], v[40:41], v[98:99], v[2:3]
	v_pk_fma_f32 v[4:5], v[40:41], v[100:101], v[4:5]
	v_pk_fma_f32 v[6:7], v[40:41], v[102:103], v[6:7]
	v_pk_fma_f32 v[8:9], v[40:41], v[104:105], v[8:9]
	v_pk_fma_f32 v[2:3], v[42:43], v[100:101], v[2:3]
	v_pk_fma_f32 v[4:5], v[42:43], v[102:103], v[4:5]
	v_pk_fma_f32 v[6:7], v[42:43], v[104:105], v[6:7]
	v_pk_fma_f32 v[8:9], v[42:43], v[106:107], v[8:9]
	v_pk_fma_f32 v[2:3], v[44:45], v[102:103], v[2:3]
	v_pk_fma_f32 v[4:5], v[44:45], v[104:105], v[4:5]
	v_pk_fma_f32 v[6:7], v[44:45], v[106:107], v[6:7]
	v_pk_fma_f32 v[8:9], v[44:45], v[108:109], v[8:9]
	v_pk_fma_f32 v[2:3], v[46:47], v[104:105], v[2:3]
	v_pk_fma_f32 v[4:5], v[46:47], v[106:107], v[4:5]
	v_pk_fma_f32 v[6:7], v[46:47], v[108:109], v[6:7]
	v_pk_fma_f32 v[8:9], v[46:47], v[110:111], v[8:9]
	v_pk_fma_f32 v[2:3], v[48:49], v[106:107], v[2:3]
	v_pk_fma_f32 v[4:5], v[48:49], v[108:109], v[4:5]
	v_pk_fma_f32 v[6:7], v[48:49], v[110:111], v[6:7]
	v_pk_fma_f32 v[8:9], v[48:49], v[112:113], v[8:9]
	v_pk_fma_f32 v[2:3], v[50:51], v[108:109], v[2:3]
	v_pk_fma_f32 v[4:5], v[50:51], v[110:111], v[4:5]
	v_pk_fma_f32 v[6:7], v[50:51], v[112:113], v[6:7]
	v_pk_fma_f32 v[8:9], v[50:51], v[114:115], v[8:9]
	v_pk_fma_f32 v[2:3], v[52:53], v[110:111], v[2:3]
	v_pk_fma_f32 v[4:5], v[52:53], v[112:113], v[4:5]
	v_pk_fma_f32 v[6:7], v[52:53], v[114:115], v[6:7]
	v_pk_fma_f32 v[8:9], v[52:53], v[116:117], v[8:9]
	v_pk_fma_f32 v[2:3], v[54:55], v[112:113], v[2:3]
	v_pk_fma_f32 v[4:5], v[54:55], v[114:115], v[4:5]
	v_pk_fma_f32 v[6:7], v[54:55], v[116:117], v[6:7]
	v_pk_fma_f32 v[8:9], v[54:55], v[118:119], v[8:9]
	v_pk_fma_f32 v[2:3], v[56:57], v[114:115], v[2:3]
	v_pk_fma_f32 v[4:5], v[56:57], v[116:117], v[4:5]
	v_pk_fma_f32 v[6:7], v[56:57], v[118:119], v[6:7]
	v_pk_fma_f32 v[8:9], v[56:57], v[120:121], v[8:9]
	v_pk_fma_f32 v[2:3], v[58:59], v[116:117], v[2:3]
	v_pk_fma_f32 v[4:5], v[58:59], v[118:119], v[4:5]
	v_pk_fma_f32 v[6:7], v[58:59], v[120:121], v[6:7]
	v_pk_fma_f32 v[8:9], v[58:59], v[122:123], v[8:9]
	v_pk_fma_f32 v[2:3], v[60:61], v[118:119], v[2:3]
	v_pk_fma_f32 v[4:5], v[60:61], v[120:121], v[4:5]
	v_pk_fma_f32 v[6:7], v[60:61], v[122:123], v[6:7]
	v_pk_fma_f32 v[8:9], v[60:61], v[124:125], v[8:9]
	v_pk_fma_f32 v[2:3], v[62:63], v[120:121], v[2:3]
	v_pk_fma_f32 v[4:5], v[62:63], v[122:123], v[4:5]
	v_pk_fma_f32 v[6:7], v[62:63], v[124:125], v[6:7]
	v_pk_fma_f32 v[8:9], v[62:63], v[126:127], v[8:9]
	v_pk_fma_f32 v[2:3], v[64:65], v[122:123], v[2:3]
	v_pk_fma_f32 v[4:5], v[64:65], v[124:125], v[4:5]
	v_pk_fma_f32 v[6:7], v[64:65], v[126:127], v[6:7]
	v_pk_fma_f32 v[8:9], v[64:65], v[128:129], v[8:9]
	v_pk_fma_f32 v[2:3], v[66:67], v[124:125], v[2:3]
	v_pk_fma_f32 v[4:5], v[66:67], v[126:127], v[4:5]
	v_pk_fma_f32 v[6:7], v[66:67], v[128:129], v[6:7]
	v_pk_fma_f32 v[8:9], v[66:67], v[130:131], v[8:9]
	v_pk_fma_f32 v[2:3], v[68:69], v[126:127], v[2:3]
	v_pk_fma_f32 v[4:5], v[68:69], v[128:129], v[4:5]
	v_pk_fma_f32 v[6:7], v[68:69], v[130:131], v[6:7]
	v_pk_fma_f32 v[8:9], v[68:69], v[132:133], v[8:9]
	v_pk_fma_f32 v[2:3], v[70:71], v[128:129], v[2:3]
	v_pk_fma_f32 v[4:5], v[70:71], v[130:131], v[4:5]
	v_pk_fma_f32 v[6:7], v[70:71], v[132:133], v[6:7]
	v_pk_fma_f32 v[8:9], v[70:71], v[134:135], v[8:9]
	v_pk_fma_f32 v[2:3], v[72:73], v[130:131], v[2:3]
	v_pk_fma_f32 v[4:5], v[72:73], v[132:133], v[4:5]
; #define LAS __attribute__((address_space(3)))
; __device__ __forceinline__ void conv_item(KP p, LAS unsigned char* lds, int l, int tile) {
;     ...
;         for (int j = 0; j < 31; ++j)
; #pragma unroll
;             for (int q = 0; q < 4; ++q) y[q] += w[j] * g[q + j];
; #pragma unroll
;         for (int q = 0; q < 4; ++q) *(LAS f32x2*)(ybuf + (blk * 4 + q) * 1024 + c0) = y[q];
; #pragma unroll
;         for (int i = 0; i < 30; ++i) g[i] = g[i + 4];
;     }
	v_pk_fma_f32 v[6:7], v[72:73], v[134:135], v[6:7]
	v_pk_fma_f32 v[8:9], v[72:73], v[136:137], v[8:9]
	v_pk_fma_f32 v[2:3], v[74:75], v[132:133], v[2:3]
	v_pk_fma_f32 v[4:5], v[74:75], v[134:135], v[4:5]
	v_pk_fma_f32 v[6:7], v[74:75], v[136:137], v[6:7]
	v_pk_fma_f32 v[8:9], v[74:75], v[138:139], v[8:9]
	v_pk_fma_f32 v[2:3], v[76:77], v[134:135], v[2:3]
	v_pk_fma_f32 v[4:5], v[76:77], v[136:137], v[4:5]
	v_add_u32_e32 v0, s64, v175
	s_add_i32 s45, s45, 4
	s_addk_i32 s64, 0x4000
	v_pk_fma_f32 v[6:7], v[76:77], v[138:139], v[6:7]
	v_pk_fma_f32 v[8:9], v[76:77], v[148:149], v[8:9]
	v_pk_fma_f32 v[2:3], v[78:79], v[136:137], v[2:3]
	v_pk_fma_f32 v[4:5], v[78:79], v[138:139], v[4:5]
	v_pk_fma_f32 v[6:7], v[78:79], v[148:149], v[6:7]
	v_pk_fma_f32 v[8:9], v[78:79], v[150:151], v[8:9]
	ds_write2st64_b64 v0, v[2:3], v[4:5] offset1:8
	ds_write2st64_b64 v0, v[6:7], v[8:9] offset0:16 offset1:24
	s_add_i32 s6, s45, 12
	s_min_i32 s6, s6, s44
	s_mulk_i32 s6, 0x2100
	v_lshl_add_u64 v[10:11], s[6:7], 1, v[82:83]
	v_add_co_u32_e32 v10, vcc, s52, v10
	s_add_i32 s66, s6, 0x2100
	s_nop 0
	v_addc_co_u32_e32 v11, vcc, 0, v11, vcc
	s_mov_b32 s67, s7
	v_mov_b64_e32 v[6:7], v[88:89]
	v_mov_b64_e32 v[88:89], v[96:97]
	v_mov_b64_e32 v[96:97], v[104:105]
	v_mov_b64_e32 v[104:105], v[112:113]
	v_mov_b64_e32 v[112:113], v[120:121]
	v_mov_b64_e32 v[120:121], v[128:129]
	v_mov_b64_e32 v[128:129], v[136:137]
	s_waitcnt vmcnt(15)
	v_lshlrev_b32_e32 v136, 16, v242
	v_and_b32_e32 v137, 0xffff0000, v242
	global_load_dword v242, v[10:11], off offset:512
	v_lshl_add_u64 v[10:11], s[66:67], 1, v[82:83]
	v_add_co_u32_e32 v10, vcc, s52, v10
	s_add_i32 s66, s6, 0x4200
	s_nop 0
	v_addc_co_u32_e32 v11, vcc, 0, v11, vcc
	v_mov_b64_e32 v[8:9], v[90:91]
	v_mov_b64_e32 v[90:91], v[98:99]
	v_mov_b64_e32 v[98:99], v[106:107]
	v_mov_b64_e32 v[106:107], v[114:115]
	v_mov_b64_e32 v[114:115], v[122:123]
	v_mov_b64_e32 v[122:123], v[130:131]
	v_mov_b64_e32 v[130:131], v[138:139]
	s_waitcnt vmcnt(15)
	v_lshlrev_b32_e32 v138, 16, v243
	v_and_b32_e32 v139, 0xffff0000, v243
	global_load_dword v243, v[10:11], off offset:512
	v_lshl_add_u64 v[10:11], s[66:67], 1, v[82:83]
	v_add_co_u32_e32 v10, vcc, s52, v10
	s_addk_i32 s6, 0x6300
	s_nop 0
	v_addc_co_u32_e32 v11, vcc, 0, v11, vcc
	v_mov_b64_e32 v[2:3], v[84:85]
	v_mov_b64_e32 v[84:85], v[92:93]
	v_mov_b64_e32 v[92:93], v[100:101]
	v_mov_b64_e32 v[100:101], v[108:109]
	v_mov_b64_e32 v[108:109], v[116:117]
	v_mov_b64_e32 v[116:117], v[124:125]
	v_mov_b64_e32 v[124:125], v[132:133]
	v_mov_b64_e32 v[132:133], v[148:149]
	s_waitcnt vmcnt(15)
	v_lshlrev_b32_e32 v148, 16, v244
	v_and_b32_e32 v149, 0xffff0000, v244
	global_load_dword v244, v[10:11], off offset:512
	v_lshl_add_u64 v[10:11], s[6:7], 1, v[82:83]
	v_add_co_u32_e32 v10, vcc, s52, v10
	v_mov_b64_e32 v[4:5], v[86:87]
	s_nop 0
	v_addc_co_u32_e32 v11, vcc, 0, v11, vcc
	v_mov_b64_e32 v[86:87], v[94:95]
	v_mov_b64_e32 v[94:95], v[102:103]
	v_mov_b64_e32 v[102:103], v[110:111]
	v_mov_b64_e32 v[110:111], v[118:119]
	v_mov_b64_e32 v[118:119], v[126:127]
	v_mov_b64_e32 v[126:127], v[134:135]
	v_mov_b64_e32 v[134:135], v[150:151]
	s_waitcnt vmcnt(15)
	v_lshlrev_b32_e32 v150, 16, v245
	v_and_b32_e32 v151, 0xffff0000, v245
	global_load_dword v245, v[10:11], off offset:512
	v_pk_fma_f32 v[2:3], v[18:19], v[2:3], v[80:81]
	v_pk_fma_f32 v[10:11], v[18:19], v[4:5], v[80:81]
	v_pk_fma_f32 v[12:13], v[18:19], v[6:7], v[80:81]
	v_pk_fma_f32 v[14:15], v[18:19], v[8:9], v[80:81]
	v_pk_fma_f32 v[2:3], v[20:21], v[4:5], v[2:3]
	v_pk_fma_f32 v[4:5], v[20:21], v[6:7], v[10:11]
	v_pk_fma_f32 v[10:11], v[20:21], v[8:9], v[12:13]
	v_pk_fma_f32 v[12:13], v[20:21], v[84:85], v[14:15]
	v_pk_fma_f32 v[2:3], v[22:23], v[6:7], v[2:3]
	v_pk_fma_f32 v[4:5], v[22:23], v[8:9], v[4:5]
	v_pk_fma_f32 v[6:7], v[22:23], v[84:85], v[10:11]
	v_pk_fma_f32 v[10:11], v[22:23], v[86:87], v[12:13]
	v_pk_fma_f32 v[2:3], v[24:25], v[8:9], v[2:3]
	v_pk_fma_f32 v[4:5], v[24:25], v[84:85], v[4:5]
	v_pk_fma_f32 v[6:7], v[24:25], v[86:87], v[6:7]
	v_pk_fma_f32 v[8:9], v[24:25], v[88:89], v[10:11]
	v_pk_fma_f32 v[2:3], v[26:27], v[84:85], v[2:3]
	v_pk_fma_f32 v[4:5], v[26:27], v[86:87], v[4:5]
	v_pk_fma_f32 v[6:7], v[26:27], v[88:89], v[6:7]
	v_pk_fma_f32 v[8:9], v[26:27], v[90:91], v[8:9]
	v_pk_fma_f32 v[2:3], v[28:29], v[86:87], v[2:3]
	v_pk_fma_f32 v[4:5], v[28:29], v[88:89], v[4:5]
	v_pk_fma_f32 v[6:7], v[28:29], v[90:91], v[6:7]
	v_pk_fma_f32 v[8:9], v[28:29], v[92:93], v[8:9]
	v_pk_fma_f32 v[2:3], v[30:31], v[88:89], v[2:3]
	v_pk_fma_f32 v[4:5], v[30:31], v[90:91], v[4:5]
	v_pk_fma_f32 v[6:7], v[30:31], v[92:93], v[6:7]
	v_pk_fma_f32 v[8:9], v[30:31], v[94:95], v[8:9]
	v_pk_fma_f32 v[2:3], v[32:33], v[90:91], v[2:3]
	v_pk_fma_f32 v[4:5], v[32:33], v[92:93], v[4:5]
	v_pk_fma_f32 v[6:7], v[32:33], v[94:95], v[6:7]
	v_pk_fma_f32 v[8:9], v[32:33], v[96:97], v[8:9]
	v_pk_fma_f32 v[2:3], v[34:35], v[92:93], v[2:3]
	v_pk_fma_f32 v[4:5], v[34:35], v[94:95], v[4:5]
	v_pk_fma_f32 v[6:7], v[34:35], v[96:97], v[6:7]
	v_pk_fma_f32 v[8:9], v[34:35], v[98:99], v[8:9]
	v_pk_fma_f32 v[2:3], v[36:37], v[94:95], v[2:3]
	v_pk_fma_f32 v[4:5], v[36:37], v[96:97], v[4:5]
	v_pk_fma_f32 v[6:7], v[36:37], v[98:99], v[6:7]
	v_pk_fma_f32 v[8:9], v[36:37], v[100:101], v[8:9]
	v_pk_fma_f32 v[2:3], v[38:39], v[96:97], v[2:3]
	v_pk_fma_f32 v[4:5], v[38:39], v[98:99], v[4:5]
	v_pk_fma_f32 v[6:7], v[38:39], v[100:101], v[6:7]
	v_pk_fma_f32 v[8:9], v[38:39], v[102:103], v[8:9]
	v_pk_fma_f32 v[2:3], v[40:41], v[98:99], v[2:3]
	v_pk_fma_f32 v[4:5], v[40:41], v[100:101], v[4:5]
	v_pk_fma_f32 v[6:7], v[40:41], v[102:103], v[6:7]
	v_pk_fma_f32 v[8:9], v[40:41], v[104:105], v[8:9]
; #define LAS __attribute__((address_space(3)))
; __device__ __forceinline__ void conv_item(KP p, LAS unsigned char* lds, int l, int tile) {
;     ...
;         for (int j = 0; j < 31; ++j)
; #pragma unroll
;             for (int q = 0; q < 4; ++q) y[q] += w[j] * g[q + j];
; #pragma unroll
;         for (int q = 0; q < 4; ++q) *(LAS f32x2*)(ybuf + (blk * 4 + q) * 1024 + c0) = y[q];
; #pragma unroll
;         for (int i = 0; i < 30; ++i) g[i] = g[i + 4];
;     }
	v_pk_fma_f32 v[2:3], v[42:43], v[100:101], v[2:3]
	v_pk_fma_f32 v[4:5], v[42:43], v[102:103], v[4:5]
	v_pk_fma_f32 v[6:7], v[42:43], v[104:105], v[6:7]
	v_pk_fma_f32 v[8:9], v[42:43], v[106:107], v[8:9]
	v_pk_fma_f32 v[2:3], v[44:45], v[102:103], v[2:3]
	v_pk_fma_f32 v[4:5], v[44:45], v[104:105], v[4:5]
	v_pk_fma_f32 v[6:7], v[44:45], v[106:107], v[6:7]
	v_pk_fma_f32 v[8:9], v[44:45], v[108:109], v[8:9]
	v_pk_fma_f32 v[2:3], v[46:47], v[104:105], v[2:3]
	v_pk_fma_f32 v[4:5], v[46:47], v[106:107], v[4:5]
	v_pk_fma_f32 v[6:7], v[46:47], v[108:109], v[6:7]
	v_pk_fma_f32 v[8:9], v[46:47], v[110:111], v[8:9]
	v_pk_fma_f32 v[2:3], v[48:49], v[106:107], v[2:3]
	v_pk_fma_f32 v[4:5], v[48:49], v[108:109], v[4:5]
	v_pk_fma_f32 v[6:7], v[48:49], v[110:111], v[6:7]
	v_pk_fma_f32 v[8:9], v[48:49], v[112:113], v[8:9]
	v_pk_fma_f32 v[2:3], v[50:51], v[108:109], v[2:3]
	v_pk_fma_f32 v[4:5], v[50:51], v[110:111], v[4:5]
	v_pk_fma_f32 v[6:7], v[50:51], v[112:113], v[6:7]
	v_pk_fma_f32 v[8:9], v[50:51], v[114:115], v[8:9]
	v_pk_fma_f32 v[2:3], v[52:53], v[110:111], v[2:3]
	v_pk_fma_f32 v[4:5], v[52:53], v[112:113], v[4:5]
	v_pk_fma_f32 v[6:7], v[52:53], v[114:115], v[6:7]
	v_pk_fma_f32 v[8:9], v[52:53], v[116:117], v[8:9]
	v_pk_fma_f32 v[2:3], v[54:55], v[112:113], v[2:3]
	v_pk_fma_f32 v[4:5], v[54:55], v[114:115], v[4:5]
	v_pk_fma_f32 v[6:7], v[54:55], v[116:117], v[6:7]
	v_pk_fma_f32 v[8:9], v[54:55], v[118:119], v[8:9]
	v_pk_fma_f32 v[2:3], v[56:57], v[114:115], v[2:3]
	v_pk_fma_f32 v[4:5], v[56:57], v[116:117], v[4:5]
	v_pk_fma_f32 v[6:7], v[56:57], v[118:119], v[6:7]
	v_pk_fma_f32 v[8:9], v[56:57], v[120:121], v[8:9]
	v_pk_fma_f32 v[2:3], v[58:59], v[116:117], v[2:3]
	v_pk_fma_f32 v[4:5], v[58:59], v[118:119], v[4:5]
	v_pk_fma_f32 v[6:7], v[58:59], v[120:121], v[6:7]
	v_pk_fma_f32 v[8:9], v[58:59], v[122:123], v[8:9]
	v_pk_fma_f32 v[2:3], v[60:61], v[118:119], v[2:3]
	v_pk_fma_f32 v[4:5], v[60:61], v[120:121], v[4:5]
	v_pk_fma_f32 v[6:7], v[60:61], v[122:123], v[6:7]
	v_pk_fma_f32 v[8:9], v[60:61], v[124:125], v[8:9]
	v_pk_fma_f32 v[2:3], v[62:63], v[120:121], v[2:3]
	v_pk_fma_f32 v[4:5], v[62:63], v[122:123], v[4:5]
	v_pk_fma_f32 v[6:7], v[62:63], v[124:125], v[6:7]
	v_pk_fma_f32 v[8:9], v[62:63], v[126:127], v[8:9]
	v_pk_fma_f32 v[2:3], v[64:65], v[122:123], v[2:3]
	v_pk_fma_f32 v[4:5], v[64:65], v[124:125], v[4:5]
	v_pk_fma_f32 v[6:7], v[64:65], v[126:127], v[6:7]
	v_pk_fma_f32 v[8:9], v[64:65], v[128:129], v[8:9]
	v_pk_fma_f32 v[2:3], v[66:67], v[124:125], v[2:3]
	v_pk_fma_f32 v[4:5], v[66:67], v[126:127], v[4:5]
	v_pk_fma_f32 v[6:7], v[66:67], v[128:129], v[6:7]
	v_pk_fma_f32 v[8:9], v[66:67], v[130:131], v[8:9]
	v_pk_fma_f32 v[2:3], v[68:69], v[126:127], v[2:3]
	v_pk_fma_f32 v[4:5], v[68:69], v[128:129], v[4:5]
	v_pk_fma_f32 v[6:7], v[68:69], v[130:131], v[6:7]
	v_pk_fma_f32 v[8:9], v[68:69], v[132:133], v[8:9]
	v_pk_fma_f32 v[2:3], v[70:71], v[128:129], v[2:3]
	v_pk_fma_f32 v[4:5], v[70:71], v[130:131], v[4:5]
	v_pk_fma_f32 v[6:7], v[70:71], v[132:133], v[6:7]
	v_pk_fma_f32 v[8:9], v[70:71], v[134:135], v[8:9]
	v_pk_fma_f32 v[2:3], v[72:73], v[130:131], v[2:3]
	v_pk_fma_f32 v[4:5], v[72:73], v[132:133], v[4:5]
	v_pk_fma_f32 v[6:7], v[72:73], v[134:135], v[6:7]
	v_pk_fma_f32 v[8:9], v[72:73], v[136:137], v[8:9]
	v_pk_fma_f32 v[2:3], v[74:75], v[132:133], v[2:3]
	v_pk_fma_f32 v[4:5], v[74:75], v[134:135], v[4:5]
	v_pk_fma_f32 v[6:7], v[74:75], v[136:137], v[6:7]
	v_pk_fma_f32 v[8:9], v[74:75], v[138:139], v[8:9]
	v_pk_fma_f32 v[2:3], v[76:77], v[134:135], v[2:3]
	v_pk_fma_f32 v[4:5], v[76:77], v[136:137], v[4:5]
	v_add_u32_e32 v0, s64, v175
	s_add_i32 s45, s45, 4
	s_addk_i32 s64, 0x4000
	v_pk_fma_f32 v[6:7], v[76:77], v[138:139], v[6:7]
	v_pk_fma_f32 v[8:9], v[76:77], v[148:149], v[8:9]
	v_pk_fma_f32 v[2:3], v[78:79], v[136:137], v[2:3]
	v_pk_fma_f32 v[4:5], v[78:79], v[138:139], v[4:5]
	v_pk_fma_f32 v[6:7], v[78:79], v[148:149], v[6:7]
	v_pk_fma_f32 v[8:9], v[78:79], v[150:151], v[8:9]
	ds_write2st64_b64 v0, v[2:3], v[4:5] offset1:8
	ds_write2st64_b64 v0, v[6:7], v[8:9] offset0:16 offset1:24
	s_add_i32 s6, s45, 12
	s_min_i32 s6, s6, s44
	s_mulk_i32 s6, 0x2100
	v_lshl_add_u64 v[10:11], s[6:7], 1, v[82:83]
	v_add_co_u32_e32 v10, vcc, s52, v10
	s_add_i32 s66, s6, 0x2100
	s_nop 0
	v_addc_co_u32_e32 v11, vcc, 0, v11, vcc
	s_mov_b32 s67, s7
	v_mov_b64_e32 v[6:7], v[88:89]
	v_mov_b64_e32 v[88:89], v[96:97]
	v_mov_b64_e32 v[96:97], v[104:105]
	v_mov_b64_e32 v[104:105], v[112:113]
	v_mov_b64_e32 v[112:113], v[120:121]
	v_mov_b64_e32 v[120:121], v[128:129]
	v_mov_b64_e32 v[128:129], v[136:137]
	s_waitcnt vmcnt(15)
	v_lshlrev_b32_e32 v136, 16, v246
	v_and_b32_e32 v137, 0xffff0000, v246
	global_load_dword v246, v[10:11], off offset:512
	v_lshl_add_u64 v[10:11], s[66:67], 1, v[82:83]
	v_add_co_u32_e32 v10, vcc, s52, v10
	s_add_i32 s66, s6, 0x4200
	s_nop 0
	v_addc_co_u32_e32 v11, vcc, 0, v11, vcc
	v_mov_b64_e32 v[8:9], v[90:91]
	v_mov_b64_e32 v[90:91], v[98:99]
	v_mov_b64_e32 v[98:99], v[106:107]
	v_mov_b64_e32 v[106:107], v[114:115]
	v_mov_b64_e32 v[114:115], v[122:123]
	v_mov_b64_e32 v[122:123], v[130:131]
	v_mov_b64_e32 v[130:131], v[138:139]
	s_waitcnt vmcnt(15)
	v_lshlrev_b32_e32 v138, 16, v247
	v_and_b32_e32 v139, 0xffff0000, v247
	global_load_dword v247, v[10:11], off offset:512
	v_lshl_add_u64 v[10:11], s[66:67], 1, v[82:83]
	v_add_co_u32_e32 v10, vcc, s52, v10
	s_addk_i32 s6, 0x6300
	s_nop 0
	v_addc_co_u32_e32 v11, vcc, 0, v11, vcc
	v_mov_b64_e32 v[2:3], v[84:85]
	v_mov_b64_e32 v[84:85], v[92:93]
	v_mov_b64_e32 v[92:93], v[100:101]
	v_mov_b64_e32 v[100:101], v[108:109]
	v_mov_b64_e32 v[108:109], v[116:117]
	v_mov_b64_e32 v[116:117], v[124:125]
	v_mov_b64_e32 v[124:125], v[132:133]
	v_mov_b64_e32 v[132:133], v[148:149]
	s_waitcnt vmcnt(15)
; __device__ __forceinline__ float bflo(unsigned w) { return __uint_as_float(w << 16); }
; __device__ __forceinline__ float bfhi(unsigned w) { return __uint_as_float(w & 0xffff0000u); }
; __device__ __forceinline__ void conv_item(KP p, LAS unsigned char* lds, int l, int tile) {
;     ...
;         for (int q = 0; q < 4; ++q) g[30 + q] = (f32x2){bflo(nv[q]), bfhi(nv[q])};
;         { const int tn = (hh == 1 && blk == 7) ? t0 + blk * 4 : t0 + (blk + 1) * 4;
; #pragma unroll
;           for (int q = 0; q < 4; ++q) nv[q] = *(const unsigned*)(hm + (size_t)(tn + q) * HMW + C_GLU); }
	v_lshlrev_b32_e32 v148, 16, v194
	v_and_b32_e32 v149, 0xffff0000, v194
	global_load_dword v194, v[10:11], off offset:512
	v_lshl_add_u64 v[10:11], s[6:7], 1, v[82:83]
	v_add_co_u32_e32 v10, vcc, s52, v10
	v_mov_b64_e32 v[4:5], v[86:87]
	s_nop 0
	v_addc_co_u32_e32 v11, vcc, 0, v11, vcc
	v_mov_b64_e32 v[86:87], v[94:95]
	v_mov_b64_e32 v[94:95], v[102:103]
	v_mov_b64_e32 v[102:103], v[110:111]
	v_mov_b64_e32 v[110:111], v[118:119]
	v_mov_b64_e32 v[118:119], v[126:127]
	v_mov_b64_e32 v[126:127], v[134:135]
	v_mov_b64_e32 v[134:135], v[150:151]
	s_waitcnt vmcnt(15)
; #define LAS __attribute__((address_space(3)))
; __device__ __forceinline__ void conv_item(KP p, LAS unsigned char* lds, int l, int tile) {
;     ...
;         for (int j = 0; j < 31; ++j)
; #pragma unroll
;             for (int q = 0; q < 4; ++q) y[q] += w[j] * g[q + j];
; #pragma unroll
;         for (int q = 0; q < 4; ++q) *(LAS f32x2*)(ybuf + (blk * 4 + q) * 1024 + c0) = y[q];
; #pragma unroll
;         for (int i = 0; i < 30; ++i) g[i] = g[i + 4];
;     }
;     __syncthreads();
	v_lshlrev_b32_e32 v150, 16, v195
	v_and_b32_e32 v151, 0xffff0000, v195
	global_load_dword v195, v[10:11], off offset:512
	v_pk_fma_f32 v[2:3], v[18:19], v[2:3], v[80:81]
	v_pk_fma_f32 v[10:11], v[18:19], v[4:5], v[80:81]
	v_pk_fma_f32 v[12:13], v[18:19], v[6:7], v[80:81]
	v_pk_fma_f32 v[14:15], v[18:19], v[8:9], v[80:81]
	v_pk_fma_f32 v[2:3], v[20:21], v[4:5], v[2:3]
	v_pk_fma_f32 v[4:5], v[20:21], v[6:7], v[10:11]
	v_pk_fma_f32 v[10:11], v[20:21], v[8:9], v[12:13]
	v_pk_fma_f32 v[12:13], v[20:21], v[84:85], v[14:15]
	v_pk_fma_f32 v[2:3], v[22:23], v[6:7], v[2:3]
	v_pk_fma_f32 v[4:5], v[22:23], v[8:9], v[4:5]
	v_pk_fma_f32 v[6:7], v[22:23], v[84:85], v[10:11]
	v_pk_fma_f32 v[10:11], v[22:23], v[86:87], v[12:13]
	v_pk_fma_f32 v[2:3], v[24:25], v[8:9], v[2:3]
	v_pk_fma_f32 v[4:5], v[24:25], v[84:85], v[4:5]
	v_pk_fma_f32 v[6:7], v[24:25], v[86:87], v[6:7]
	v_pk_fma_f32 v[8:9], v[24:25], v[88:89], v[10:11]
	v_pk_fma_f32 v[2:3], v[26:27], v[84:85], v[2:3]
	v_pk_fma_f32 v[4:5], v[26:27], v[86:87], v[4:5]
	v_pk_fma_f32 v[6:7], v[26:27], v[88:89], v[6:7]
	v_pk_fma_f32 v[8:9], v[26:27], v[90:91], v[8:9]
	v_pk_fma_f32 v[2:3], v[28:29], v[86:87], v[2:3]
	v_pk_fma_f32 v[4:5], v[28:29], v[88:89], v[4:5]
	v_pk_fma_f32 v[6:7], v[28:29], v[90:91], v[6:7]
	v_pk_fma_f32 v[8:9], v[28:29], v[92:93], v[8:9]
	v_pk_fma_f32 v[2:3], v[30:31], v[88:89], v[2:3]
	v_pk_fma_f32 v[4:5], v[30:31], v[90:91], v[4:5]
	v_pk_fma_f32 v[6:7], v[30:31], v[92:93], v[6:7]
	v_pk_fma_f32 v[8:9], v[30:31], v[94:95], v[8:9]
	v_pk_fma_f32 v[2:3], v[32:33], v[90:91], v[2:3]
	v_pk_fma_f32 v[4:5], v[32:33], v[92:93], v[4:5]
	v_pk_fma_f32 v[6:7], v[32:33], v[94:95], v[6:7]
	v_pk_fma_f32 v[8:9], v[32:33], v[96:97], v[8:9]
	v_pk_fma_f32 v[2:3], v[34:35], v[92:93], v[2:3]
	v_pk_fma_f32 v[4:5], v[34:35], v[94:95], v[4:5]
	v_pk_fma_f32 v[6:7], v[34:35], v[96:97], v[6:7]
	v_pk_fma_f32 v[8:9], v[34:35], v[98:99], v[8:9]
	v_pk_fma_f32 v[2:3], v[36:37], v[94:95], v[2:3]
	v_pk_fma_f32 v[4:5], v[36:37], v[96:97], v[4:5]
	v_pk_fma_f32 v[6:7], v[36:37], v[98:99], v[6:7]
	v_pk_fma_f32 v[8:9], v[36:37], v[100:101], v[8:9]
	v_pk_fma_f32 v[2:3], v[38:39], v[96:97], v[2:3]
	v_pk_fma_f32 v[4:5], v[38:39], v[98:99], v[4:5]
	v_pk_fma_f32 v[6:7], v[38:39], v[100:101], v[6:7]
	v_pk_fma_f32 v[8:9], v[38:39], v[102:103], v[8:9]
	v_pk_fma_f32 v[2:3], v[40:41], v[98:99], v[2:3]
	v_pk_fma_f32 v[4:5], v[40:41], v[100:101], v[4:5]
	v_pk_fma_f32 v[6:7], v[40:41], v[102:103], v[6:7]
	v_pk_fma_f32 v[8:9], v[40:41], v[104:105], v[8:9]
	v_pk_fma_f32 v[2:3], v[42:43], v[100:101], v[2:3]
	v_pk_fma_f32 v[4:5], v[42:43], v[102:103], v[4:5]
	v_pk_fma_f32 v[6:7], v[42:43], v[104:105], v[6:7]
	v_pk_fma_f32 v[8:9], v[42:43], v[106:107], v[8:9]
	v_pk_fma_f32 v[2:3], v[44:45], v[102:103], v[2:3]
	v_pk_fma_f32 v[4:5], v[44:45], v[104:105], v[4:5]
	v_pk_fma_f32 v[6:7], v[44:45], v[106:107], v[6:7]
	v_pk_fma_f32 v[8:9], v[44:45], v[108:109], v[8:9]
	v_pk_fma_f32 v[2:3], v[46:47], v[104:105], v[2:3]
	v_pk_fma_f32 v[4:5], v[46:47], v[106:107], v[4:5]
	v_pk_fma_f32 v[6:7], v[46:47], v[108:109], v[6:7]
	v_pk_fma_f32 v[8:9], v[46:47], v[110:111], v[8:9]
	v_pk_fma_f32 v[2:3], v[48:49], v[106:107], v[2:3]
	v_pk_fma_f32 v[4:5], v[48:49], v[108:109], v[4:5]
	v_pk_fma_f32 v[6:7], v[48:49], v[110:111], v[6:7]
	v_pk_fma_f32 v[8:9], v[48:49], v[112:113], v[8:9]
	v_pk_fma_f32 v[2:3], v[50:51], v[108:109], v[2:3]
	v_pk_fma_f32 v[4:5], v[50:51], v[110:111], v[4:5]
	v_pk_fma_f32 v[6:7], v[50:51], v[112:113], v[6:7]
	v_pk_fma_f32 v[8:9], v[50:51], v[114:115], v[8:9]
	v_pk_fma_f32 v[2:3], v[52:53], v[110:111], v[2:3]
	v_pk_fma_f32 v[4:5], v[52:53], v[112:113], v[4:5]
	v_pk_fma_f32 v[6:7], v[52:53], v[114:115], v[6:7]
	v_pk_fma_f32 v[8:9], v[52:53], v[116:117], v[8:9]
	v_pk_fma_f32 v[2:3], v[54:55], v[112:113], v[2:3]
	v_pk_fma_f32 v[4:5], v[54:55], v[114:115], v[4:5]
	v_pk_fma_f32 v[6:7], v[54:55], v[116:117], v[6:7]
	v_pk_fma_f32 v[8:9], v[54:55], v[118:119], v[8:9]
	v_pk_fma_f32 v[2:3], v[56:57], v[114:115], v[2:3]
	v_pk_fma_f32 v[4:5], v[56:57], v[116:117], v[4:5]
	v_pk_fma_f32 v[6:7], v[56:57], v[118:119], v[6:7]
	v_pk_fma_f32 v[8:9], v[56:57], v[120:121], v[8:9]
	v_pk_fma_f32 v[2:3], v[58:59], v[116:117], v[2:3]
	v_pk_fma_f32 v[4:5], v[58:59], v[118:119], v[4:5]
	v_pk_fma_f32 v[6:7], v[58:59], v[120:121], v[6:7]
	v_pk_fma_f32 v[8:9], v[58:59], v[122:123], v[8:9]
	v_pk_fma_f32 v[2:3], v[60:61], v[118:119], v[2:3]
	v_pk_fma_f32 v[4:5], v[60:61], v[120:121], v[4:5]
	v_pk_fma_f32 v[6:7], v[60:61], v[122:123], v[6:7]
	v_pk_fma_f32 v[8:9], v[60:61], v[124:125], v[8:9]
	v_pk_fma_f32 v[2:3], v[62:63], v[120:121], v[2:3]
	v_pk_fma_f32 v[4:5], v[62:63], v[122:123], v[4:5]
	v_pk_fma_f32 v[6:7], v[62:63], v[124:125], v[6:7]
	v_pk_fma_f32 v[8:9], v[62:63], v[126:127], v[8:9]
	v_pk_fma_f32 v[2:3], v[64:65], v[122:123], v[2:3]
	v_pk_fma_f32 v[4:5], v[64:65], v[124:125], v[4:5]
	v_pk_fma_f32 v[6:7], v[64:65], v[126:127], v[6:7]
	v_pk_fma_f32 v[8:9], v[64:65], v[128:129], v[8:9]
	v_pk_fma_f32 v[2:3], v[66:67], v[124:125], v[2:3]
	v_pk_fma_f32 v[4:5], v[66:67], v[126:127], v[4:5]
	v_pk_fma_f32 v[6:7], v[66:67], v[128:129], v[6:7]
	v_pk_fma_f32 v[8:9], v[66:67], v[130:131], v[8:9]
	v_pk_fma_f32 v[2:3], v[68:69], v[126:127], v[2:3]
	v_pk_fma_f32 v[4:5], v[68:69], v[128:129], v[4:5]
	v_pk_fma_f32 v[6:7], v[68:69], v[130:131], v[6:7]
	v_pk_fma_f32 v[8:9], v[68:69], v[132:133], v[8:9]
	v_pk_fma_f32 v[2:3], v[70:71], v[128:129], v[2:3]
	v_pk_fma_f32 v[4:5], v[70:71], v[130:131], v[4:5]
	v_pk_fma_f32 v[6:7], v[70:71], v[132:133], v[6:7]
	v_pk_fma_f32 v[8:9], v[70:71], v[134:135], v[8:9]
	v_pk_fma_f32 v[2:3], v[72:73], v[130:131], v[2:3]
	v_pk_fma_f32 v[4:5], v[72:73], v[132:133], v[4:5]
	v_pk_fma_f32 v[6:7], v[72:73], v[134:135], v[6:7]
	v_pk_fma_f32 v[8:9], v[72:73], v[136:137], v[8:9]
	v_pk_fma_f32 v[2:3], v[74:75], v[132:133], v[2:3]
	v_pk_fma_f32 v[4:5], v[74:75], v[134:135], v[4:5]
	v_pk_fma_f32 v[6:7], v[74:75], v[136:137], v[6:7]
	v_pk_fma_f32 v[8:9], v[74:75], v[138:139], v[8:9]
	v_pk_fma_f32 v[2:3], v[76:77], v[134:135], v[2:3]
	v_pk_fma_f32 v[4:5], v[76:77], v[136:137], v[4:5]
	v_add_u32_e32 v0, s64, v175
	s_add_i32 s45, s45, 4
	s_addk_i32 s64, 0x4000
	v_pk_fma_f32 v[6:7], v[76:77], v[138:139], v[6:7]
	v_pk_fma_f32 v[8:9], v[76:77], v[148:149], v[8:9]
	v_pk_fma_f32 v[2:3], v[78:79], v[136:137], v[2:3]
	v_pk_fma_f32 v[4:5], v[78:79], v[138:139], v[4:5]
	s_cmp_lg_u32 s64, 0x20000
	v_pk_fma_f32 v[6:7], v[78:79], v[148:149], v[6:7]
	v_pk_fma_f32 v[8:9], v[78:79], v[150:151], v[8:9]
	ds_write2st64_b64 v0, v[2:3], v[4:5] offset1:8
	ds_write2st64_b64 v0, v[6:7], v[8:9] offset0:16 offset1:24
	s_cbranch_scc1 .LBB0_462
	s_add_i32 s6, s62, s63
	s_add_u32 s42, s46, s6
	s_addc_u32 s43, s61, 0
	s_mul_i32 s6, s43, 0x4200
	v_mad_u64_u32 v[160:161], s[44:45], s42, v171, v[156:157]
	s_lshl_b64 s[42:43], s[42:43], 11
	v_add_u32_e32 v161, s6, v161
	v_lshl_add_u64 v[162:163], v[158:159], 0, s[42:43]
	s_mov_b32 s6, 0
	s_waitcnt lgkmcnt(0)
	s_barrier

; __global__ void __launch_bounds__(512, 2) fwd_megakernel(Params p_unused) {
;     extern __shared__ __attribute__((aligned(16))) unsigned char lds_raw[];
	.amdhsa_kernel _Z14fwd_megakernel6Params
		.amdhsa_group_segment_fixed_size 0
		.amdhsa_private_segment_fixed_size 0
		.amdhsa_kernarg_size 424
		.amdhsa_user_sgpr_count 2
		.amdhsa_user_sgpr_dispatch_ptr 0
		.amdhsa_user_sgpr_queue_ptr 0
		.amdhsa_user_sgpr_kernarg_segment_ptr 1
		.amdhsa_user_sgpr_dispatch_id 0
		.amdhsa_user_sgpr_kernarg_preload_length 0
		.amdhsa_user_sgpr_kernarg_preload_offset 0
		.amdhsa_user_sgpr_private_segment_size 0
		.amdhsa_uses_dynamic_stack 0
		.amdhsa_enable_private_segment 0
		.amdhsa_system_sgpr_workgroup_id_x 1
		.amdhsa_system_sgpr_workgroup_id_y 0
		.amdhsa_system_sgpr_workgroup_id_z 0
		.amdhsa_system_sgpr_workgroup_info 0
		.amdhsa_system_vgpr_workitem_id 2
		.amdhsa_next_free_vgpr 248
		.amdhsa_next_free_sgpr 98
		.amdhsa_accum_offset 248
		.amdhsa_reserve_vcc 1
		.amdhsa_float_round_mode_32 0
		.amdhsa_float_round_mode_16_64 0
		.amdhsa_float_denorm_mode_32 3
		.amdhsa_float_denorm_mode_16_64 3
		.amdhsa_dx10_clamp 1
		.amdhsa_ieee_mode 1
		.amdhsa_fp16_overflow 0
		.amdhsa_tg_split 0
		.amdhsa_exception_fp_ieee_invalid_op 0
		.amdhsa_exception_fp_denorm_src 0
		.amdhsa_exception_fp_ieee_div_zero 0
		.amdhsa_exception_fp_ieee_overflow 0
		.amdhsa_exception_fp_ieee_underflow 0
		.amdhsa_exception_fp_ieee_inexact 0
		.amdhsa_exception_int_div_zero 0
	.end_amdhsa_kernel

; __global__ void __launch_bounds__(512, 2) fwd_megakernel(Params p_unused) {
;     extern __shared__ __attribute__((aligned(16))) unsigned char lds_raw[];
amdhsa.kernels:
  - .agpr_count:     0
    .args:
      - .offset:         0
        .size:           168
        .value_kind:     by_value
      - .offset:         168
        .size:           4
        .value_kind:     hidden_block_count_x
      - .offset:         172
        .size:           4
        .value_kind:     hidden_block_count_y
      - .offset:         176
        .size:           4
        .value_kind:     hidden_block_count_z
      - .offset:         180
        .size:           2
        .value_kind:     hidden_group_size_x
      - .offset:         182
        .size:           2
        .value_kind:     hidden_group_size_y
      - .offset:         184
        .size:           2
        .value_kind:     hidden_group_size_z
      - .offset:         186
        .size:           2
        .value_kind:     hidden_remainder_x
      - .offset:         188
        .size:           2
        .value_kind:     hidden_remainder_y
      - .offset:         190
        .size:           2
        .value_kind:     hidden_remainder_z
      - .offset:         208
        .size:           8
        .value_kind:     hidden_global_offset_x
      - .offset:         216
        .size:           8
        .value_kind:     hidden_global_offset_y
      - .offset:         224
        .size:           8
        .value_kind:     hidden_global_offset_z
      - .offset:         232
        .size:           2
        .value_kind:     hidden_grid_dims
      - .offset:         256
        .size:           8
        .value_kind:     hidden_multigrid_sync_arg
      - .offset:         288
        .size:           4
        .value_kind:     hidden_dynamic_lds_size
    .group_segment_fixed_size: 0
    .kernarg_segment_align: 8
    .kernarg_segment_size: 424
    .language:       OpenCL C
    .language_version:
      - 2
      - 0
    .max_flat_workgroup_size: 512
    .name:           _Z14fwd_megakernel6Params
    .private_segment_fixed_size: 0
    .sgpr_count:     104
    .sgpr_spill_count: 114
    .symbol:         _Z14fwd_megakernel6Params.kd
    .uniform_work_group_size: 1
    .uses_dynamic_stack: false
    .vgpr_count:     248
    .vgpr_spill_count: 0
    .wavefront_size: 64
